# plus proj0/proj1 epilogue: rstd loads hoisted to tile start, cs/sqrt(x) via v_rsq_f32*cs instead of IEEE sqrt+div sequences
# baseline (speedup 1.0000x reference)
.LBB0_151:
	s_ashr_i32 s37, s36, 31
	s_lshl_b64 s[38:39], s[36:37], 20
	s_add_u32 s38, s33, s38
	s_addc_u32 s39, s60, s39
	s_and_b64 s[40:41], s[0:1], exec
	s_cselect_b32 s37, s39, s45
	s_cselect_b32 s83, s38, s44
	s_ashr_i32 s35, s34, 31
	s_lshl_b64 s[40:41], s[34:35], 20
	s_add_u32 s40, s61, s40
	s_addc_u32 s41, s64, s41
	s_and_b64 s[48:49], s[0:1], exec
	s_cselect_b32 s35, s41, s47
	s_cselect_b32 s84, s40, s46
	s_add_u32 s44, s44, 0x80080
	s_addc_u32 s45, s45, 0
	s_add_u32 s85, s46, 0x100
	v_mov_b32_e32 v0, 0
	s_addc_u32 s86, s47, 0
	s_mov_b32 s87, -2
	v_mov_b32_e32 v1, v0
	v_mov_b32_e32 v2, v0
	v_mov_b32_e32 v3, v0
	v_mov_b32_e32 v4, v0
	v_mov_b32_e32 v5, v0
	v_mov_b32_e32 v6, v0
	v_mov_b32_e32 v7, v0
	v_mov_b32_e32 v16, v0
	v_mov_b32_e32 v17, v0
	v_mov_b32_e32 v18, v0
	v_mov_b32_e32 v19, v0
	v_mov_b32_e32 v20, v0
	v_mov_b32_e32 v21, v0
	v_mov_b32_e32 v22, v0
	v_mov_b32_e32 v23, v0
	v_mov_b32_e32 v32, v0
	v_mov_b32_e32 v33, v0
	v_mov_b32_e32 v34, v0
	v_mov_b32_e32 v35, v0
	v_mov_b32_e32 v36, v0
	v_mov_b32_e32 v37, v0
	v_mov_b32_e32 v38, v0
	v_mov_b32_e32 v39, v0
	v_mov_b32_e32 v48, v0
	v_mov_b32_e32 v49, v0
	v_mov_b32_e32 v50, v0
	v_mov_b32_e32 v51, v0
	v_mov_b32_e32 v52, v0
	v_mov_b32_e32 v53, v0
	v_mov_b32_e32 v54, v0
	v_mov_b32_e32 v55, v0
	v_mov_b32_e32 v8, v0
	v_mov_b32_e32 v9, v0
	v_mov_b32_e32 v10, v0
	v_mov_b32_e32 v11, v0
	v_mov_b32_e32 v12, v0
	v_mov_b32_e32 v13, v0
	v_mov_b32_e32 v14, v0
	v_mov_b32_e32 v15, v0
	v_mov_b32_e32 v24, v0
	v_mov_b32_e32 v25, v0
	v_mov_b32_e32 v26, v0
	v_mov_b32_e32 v27, v0
	v_mov_b32_e32 v28, v0
	v_mov_b32_e32 v29, v0
	v_mov_b32_e32 v30, v0
	v_mov_b32_e32 v31, v0
	v_mov_b32_e32 v40, v0
	v_mov_b32_e32 v41, v0
	v_mov_b32_e32 v42, v0
	v_mov_b32_e32 v43, v0
	v_mov_b32_e32 v44, v0
	v_mov_b32_e32 v45, v0
	v_mov_b32_e32 v46, v0
	v_mov_b32_e32 v47, v0
	v_mov_b32_e32 v56, v0
	v_mov_b32_e32 v57, v0
	v_mov_b32_e32 v58, v0
	v_mov_b32_e32 v59, v0
	v_mov_b32_e32 v60, v0
	v_mov_b32_e32 v61, v0
	v_mov_b32_e32 v62, v0
	v_mov_b32_e32 v63, v0
	v_mov_b32_e32 v64, v0
	v_mov_b32_e32 v65, v0
	v_mov_b32_e32 v66, v0
	v_mov_b32_e32 v67, v0
	v_mov_b32_e32 v68, v0
	v_mov_b32_e32 v69, v0
	v_mov_b32_e32 v70, v0
	v_mov_b32_e32 v71, v0
	v_mov_b32_e32 v80, v0
	v_mov_b32_e32 v81, v0
	v_mov_b32_e32 v82, v0
	v_mov_b32_e32 v83, v0
	v_mov_b32_e32 v84, v0
	v_mov_b32_e32 v85, v0
	v_mov_b32_e32 v86, v0
	v_mov_b32_e32 v87, v0
	v_mov_b32_e32 v96, v0
	v_mov_b32_e32 v97, v0
	v_mov_b32_e32 v98, v0
	v_mov_b32_e32 v99, v0
	v_mov_b32_e32 v100, v0
	v_mov_b32_e32 v101, v0
	v_mov_b32_e32 v102, v0
	v_mov_b32_e32 v103, v0
	v_mov_b32_e32 v112, v0
	v_mov_b32_e32 v113, v0
	v_mov_b32_e32 v114, v0
	v_mov_b32_e32 v115, v0
	v_mov_b32_e32 v116, v0
	v_mov_b32_e32 v117, v0
	v_mov_b32_e32 v118, v0
	v_mov_b32_e32 v119, v0
	v_mov_b32_e32 v72, v0
	v_mov_b32_e32 v73, v0
	v_mov_b32_e32 v74, v0
	v_mov_b32_e32 v75, v0
	v_mov_b32_e32 v76, v0
	v_mov_b32_e32 v77, v0
	v_mov_b32_e32 v78, v0
	v_mov_b32_e32 v79, v0
	v_mov_b32_e32 v88, v0
	v_mov_b32_e32 v89, v0
	v_mov_b32_e32 v90, v0
	v_mov_b32_e32 v91, v0
	v_mov_b32_e32 v92, v0
	v_mov_b32_e32 v93, v0
	v_mov_b32_e32 v94, v0
	v_mov_b32_e32 v95, v0
	v_mov_b32_e32 v104, v0
	v_mov_b32_e32 v105, v0
	v_mov_b32_e32 v106, v0
	v_mov_b32_e32 v107, v0
	v_mov_b32_e32 v108, v0
	v_mov_b32_e32 v109, v0
	v_mov_b32_e32 v110, v0
	v_mov_b32_e32 v111, v0
	v_mov_b32_e32 v120, v0
	v_mov_b32_e32 v121, v0
	v_mov_b32_e32 v122, v0
	v_mov_b32_e32 v123, v0
	v_mov_b32_e32 v124, v0
	v_mov_b32_e32 v125, v0
	v_mov_b32_e32 v126, v0
	v_mov_b32_e32 v127, v0
	v_lshl_add_u32 v250, s4, 8, v152
	v_ashrrev_i32_e32 v251, 31, v250
	v_lshl_add_u64 v[250:251], v[250:251], 2, s[54:55]
	global_load_dword v242, v[250:251], off
	global_load_dword v243, v[250:251], off offset:64
	global_load_dword v244, v[250:251], off offset:128
	global_load_dword v245, v[250:251], off offset:192
	global_load_dword v246, v[250:251], off offset:512
	global_load_dword v247, v[250:251], off offset:576
	global_load_dword v248, v[250:251], off offset:640
	global_load_dword v249, v[250:251], off offset:704

.LBB0_155:
	v_lshl_add_u32 v144, s4, 8, v152
	v_ashrrev_i32_e32 v145, 31, v144
	v_lshl_add_u64 v[150:151], v[144:145], 2, s[54:55]
	s_nop 0
	s_cmp_lt_i32 s5, 4
	s_cselect_b64 vcc, -1, 0
	v_cndmask_b32_e32 v145, 1.0, v160, vcc
	v_mov_b64_e32 v[148:149], s[20:21]
	v_lshl_or_b32 v146, s5, 8, v154
	v_ashrrev_i32_e32 v147, 31, v146
	v_lshlrev_b64 v[146:147], 1, v[146:147]
	s_nop 0
	v_fmamk_f32 v161, v242, 0x3a000000, v158
	v_rsq_f32_e32 v252, v161
	s_nop 0
	v_mul_f32_e32 v252, v252, v145
	v_mad_i64_i32 v[162:163], s[4:5], v144, s82, v[148:149]
	v_lshl_add_u64 v[162:163], v[162:163], 0, v[146:147]
	v_pk_mul_f32 v[126:127], v[126:127], v[252:253] op_sel_hi:[1,0]
	v_pk_mul_f32 v[124:125], v[124:125], v[252:253] op_sel_hi:[1,0]
	v_pk_mul_f32 v[122:123], v[122:123], v[252:253] op_sel_hi:[1,0]
	v_pk_mul_f32 v[120:121], v[120:121], v[252:253] op_sel_hi:[1,0]
	v_pk_mul_f32 v[118:119], v[118:119], v[252:253] op_sel_hi:[1,0]
	v_pk_mul_f32 v[116:117], v[116:117], v[252:253] op_sel_hi:[1,0]
	v_pk_mul_f32 v[166:167], v[114:115], v[252:253] op_sel_hi:[1,0]
	v_pk_mul_f32 v[164:165], v[112:113], v[252:253] op_sel_hi:[1,0]
	v_cvt_pk_bf16_f32 v112, v124, v125
	v_cvt_pk_bf16_f32 v113, v126, v127
	v_cvt_pk_bf16_f32 v114, v120, v121
	v_cvt_pk_bf16_f32 v115, v122, v123
	v_cvt_pk_bf16_f32 v116, v116, v117
	v_cvt_pk_bf16_f32 v117, v118, v119
	v_cvt_pk_bf16_f32 v118, v164, v165
	v_cvt_pk_bf16_f32 v119, v166, v167
	global_store_dwordx4 v[162:163], v[112:115], off
	global_store_dwordx4 v[162:163], v[116:119], off offset:256
	s_nop 0
	s_nop 0
	v_fmamk_f32 v112, v243, 0x3a000000, v158
	v_rsq_f32_e32 v252, v112
	s_nop 0
	v_mul_f32_e32 v252, v252, v145
	v_or_b32_e32 v112, 16, v144
	v_mad_i64_i32 v[112:113], s[4:5], v112, s82, v[148:149]
	v_lshl_add_u64 v[112:113], v[112:113], 0, v[146:147]
	v_pk_mul_f32 v[110:111], v[110:111], v[252:253] op_sel_hi:[1,0]
	v_pk_mul_f32 v[108:109], v[108:109], v[252:253] op_sel_hi:[1,0]
	v_pk_mul_f32 v[106:107], v[106:107], v[252:253] op_sel_hi:[1,0]
	v_pk_mul_f32 v[104:105], v[104:105], v[252:253] op_sel_hi:[1,0]
	v_pk_mul_f32 v[102:103], v[102:103], v[252:253] op_sel_hi:[1,0]
	v_pk_mul_f32 v[100:101], v[100:101], v[252:253] op_sel_hi:[1,0]
	v_pk_mul_f32 v[116:117], v[98:99], v[252:253] op_sel_hi:[1,0]
	v_pk_mul_f32 v[114:115], v[96:97], v[252:253] op_sel_hi:[1,0]
	v_cvt_pk_bf16_f32 v96, v108, v109
	v_cvt_pk_bf16_f32 v97, v110, v111
	v_cvt_pk_bf16_f32 v98, v104, v105
	v_cvt_pk_bf16_f32 v99, v106, v107
	v_cvt_pk_bf16_f32 v100, v100, v101
	v_cvt_pk_bf16_f32 v101, v102, v103
	v_cvt_pk_bf16_f32 v102, v114, v115
	v_cvt_pk_bf16_f32 v103, v116, v117
	global_store_dwordx4 v[112:113], v[96:99], off
	global_store_dwordx4 v[112:113], v[100:103], off offset:256
	s_nop 0
	s_nop 0
	v_fmamk_f32 v96, v244, 0x3a000000, v158
	v_rsq_f32_e32 v252, v96
	s_nop 0
	v_mul_f32_e32 v252, v252, v145
	v_or_b32_e32 v96, 32, v144
	v_mad_i64_i32 v[96:97], s[4:5], v96, s82, v[148:149]
	v_lshl_add_u64 v[96:97], v[96:97], 0, v[146:147]
	v_pk_mul_f32 v[94:95], v[94:95], v[252:253] op_sel_hi:[1,0]
	v_pk_mul_f32 v[92:93], v[92:93], v[252:253] op_sel_hi:[1,0]
	v_pk_mul_f32 v[90:91], v[90:91], v[252:253] op_sel_hi:[1,0]
	v_pk_mul_f32 v[88:89], v[88:89], v[252:253] op_sel_hi:[1,0]
	v_pk_mul_f32 v[86:87], v[86:87], v[252:253] op_sel_hi:[1,0]
	v_pk_mul_f32 v[84:85], v[84:85], v[252:253] op_sel_hi:[1,0]
	v_pk_mul_f32 v[100:101], v[82:83], v[252:253] op_sel_hi:[1,0]
	v_pk_mul_f32 v[98:99], v[80:81], v[252:253] op_sel_hi:[1,0]
	v_cvt_pk_bf16_f32 v80, v92, v93
	v_cvt_pk_bf16_f32 v81, v94, v95
	v_cvt_pk_bf16_f32 v82, v88, v89
	v_cvt_pk_bf16_f32 v83, v90, v91
	v_cvt_pk_bf16_f32 v84, v84, v85
	v_cvt_pk_bf16_f32 v85, v86, v87
	v_cvt_pk_bf16_f32 v86, v98, v99
	v_cvt_pk_bf16_f32 v87, v100, v101
	global_store_dwordx4 v[96:97], v[80:83], off
	global_store_dwordx4 v[96:97], v[84:87], off offset:256
	s_nop 0
	s_nop 0
	v_fmamk_f32 v80, v245, 0x3a000000, v158
	v_rsq_f32_e32 v252, v80
	s_nop 0
	v_mul_f32_e32 v252, v252, v145
	v_or_b32_e32 v80, 48, v144
	v_mad_i64_i32 v[80:81], s[4:5], v80, s82, v[148:149]
	v_lshl_add_u64 v[80:81], v[80:81], 0, v[146:147]
	v_pk_mul_f32 v[78:79], v[78:79], v[252:253] op_sel_hi:[1,0]
	v_pk_mul_f32 v[76:77], v[76:77], v[252:253] op_sel_hi:[1,0]
	v_pk_mul_f32 v[74:75], v[74:75], v[252:253] op_sel_hi:[1,0]
	v_pk_mul_f32 v[72:73], v[72:73], v[252:253] op_sel_hi:[1,0]
	v_pk_mul_f32 v[70:71], v[70:71], v[252:253] op_sel_hi:[1,0]
	v_pk_mul_f32 v[68:69], v[68:69], v[252:253] op_sel_hi:[1,0]
	v_pk_mul_f32 v[84:85], v[66:67], v[252:253] op_sel_hi:[1,0]
	v_pk_mul_f32 v[82:83], v[64:65], v[252:253] op_sel_hi:[1,0]
	v_cvt_pk_bf16_f32 v64, v76, v77
	v_cvt_pk_bf16_f32 v65, v78, v79
	v_cvt_pk_bf16_f32 v66, v72, v73
	v_cvt_pk_bf16_f32 v67, v74, v75
	v_cvt_pk_bf16_f32 v68, v68, v69
	v_cvt_pk_bf16_f32 v69, v70, v71
	v_cvt_pk_bf16_f32 v70, v82, v83
	v_cvt_pk_bf16_f32 v71, v84, v85
	global_store_dwordx4 v[80:81], v[64:67], off
	global_store_dwordx4 v[80:81], v[68:71], off offset:256
	s_nop 0
	s_nop 0
	v_fmamk_f32 v64, v246, 0x3a000000, v158
	v_rsq_f32_e32 v252, v64
	s_nop 0
	v_mul_f32_e32 v252, v252, v145
	v_add_u32_e32 v64, 0x80, v144
	v_mad_i64_i32 v[64:65], s[4:5], v64, s82, v[148:149]
	v_lshl_add_u64 v[64:65], v[64:65], 0, v[146:147]
	v_pk_mul_f32 v[62:63], v[62:63], v[252:253] op_sel_hi:[1,0]
	v_pk_mul_f32 v[60:61], v[60:61], v[252:253] op_sel_hi:[1,0]
	v_pk_mul_f32 v[58:59], v[58:59], v[252:253] op_sel_hi:[1,0]
	v_pk_mul_f32 v[56:57], v[56:57], v[252:253] op_sel_hi:[1,0]
	v_pk_mul_f32 v[54:55], v[54:55], v[252:253] op_sel_hi:[1,0]
	v_pk_mul_f32 v[52:53], v[52:53], v[252:253] op_sel_hi:[1,0]
	v_pk_mul_f32 v[68:69], v[50:51], v[252:253] op_sel_hi:[1,0]
	v_pk_mul_f32 v[66:67], v[48:49], v[252:253] op_sel_hi:[1,0]
	v_cvt_pk_bf16_f32 v48, v60, v61
	v_cvt_pk_bf16_f32 v49, v62, v63
	v_cvt_pk_bf16_f32 v50, v56, v57
	v_cvt_pk_bf16_f32 v51, v58, v59
	v_cvt_pk_bf16_f32 v52, v52, v53
	v_cvt_pk_bf16_f32 v53, v54, v55
	v_cvt_pk_bf16_f32 v54, v66, v67
	v_cvt_pk_bf16_f32 v55, v68, v69
	global_store_dwordx4 v[64:65], v[48:51], off
	global_store_dwordx4 v[64:65], v[52:55], off offset:256
	s_nop 0
	s_nop 0
	v_fmamk_f32 v48, v247, 0x3a000000, v158
	v_rsq_f32_e32 v252, v48
	s_nop 0
	v_mul_f32_e32 v252, v252, v145
	v_add_u32_e32 v48, 0x90, v144
	v_mad_i64_i32 v[48:49], s[4:5], v48, s82, v[148:149]
	v_lshl_add_u64 v[48:49], v[48:49], 0, v[146:147]
	v_pk_mul_f32 v[46:47], v[46:47], v[252:253] op_sel_hi:[1,0]
	v_pk_mul_f32 v[44:45], v[44:45], v[252:253] op_sel_hi:[1,0]
	v_pk_mul_f32 v[42:43], v[42:43], v[252:253] op_sel_hi:[1,0]
	v_pk_mul_f32 v[40:41], v[40:41], v[252:253] op_sel_hi:[1,0]
	v_pk_mul_f32 v[38:39], v[38:39], v[252:253] op_sel_hi:[1,0]
	v_pk_mul_f32 v[36:37], v[36:37], v[252:253] op_sel_hi:[1,0]
	v_pk_mul_f32 v[52:53], v[34:35], v[252:253] op_sel_hi:[1,0]
	v_pk_mul_f32 v[50:51], v[32:33], v[252:253] op_sel_hi:[1,0]
	v_cvt_pk_bf16_f32 v32, v44, v45
	v_cvt_pk_bf16_f32 v33, v46, v47
	v_cvt_pk_bf16_f32 v34, v40, v41
	v_cvt_pk_bf16_f32 v35, v42, v43
	v_cvt_pk_bf16_f32 v36, v36, v37
	v_cvt_pk_bf16_f32 v37, v38, v39
	v_cvt_pk_bf16_f32 v38, v50, v51
	v_cvt_pk_bf16_f32 v39, v52, v53
	global_store_dwordx4 v[48:49], v[32:35], off
	global_store_dwordx4 v[48:49], v[36:39], off offset:256
	s_nop 0
	s_nop 0
	v_fmamk_f32 v32, v248, 0x3a000000, v158
	v_rsq_f32_e32 v252, v32
	s_nop 0
	v_mul_f32_e32 v252, v252, v145
	v_add_u32_e32 v32, 0xa0, v144
	v_mad_i64_i32 v[32:33], s[4:5], v32, s82, v[148:149]
	v_lshl_add_u64 v[32:33], v[32:33], 0, v[146:147]
	v_pk_mul_f32 v[30:31], v[30:31], v[252:253] op_sel_hi:[1,0]
	v_pk_mul_f32 v[28:29], v[28:29], v[252:253] op_sel_hi:[1,0]
	v_pk_mul_f32 v[26:27], v[26:27], v[252:253] op_sel_hi:[1,0]
	v_pk_mul_f32 v[24:25], v[24:25], v[252:253] op_sel_hi:[1,0]
	v_pk_mul_f32 v[22:23], v[22:23], v[252:253] op_sel_hi:[1,0]
	v_pk_mul_f32 v[20:21], v[20:21], v[252:253] op_sel_hi:[1,0]
	v_pk_mul_f32 v[36:37], v[18:19], v[252:253] op_sel_hi:[1,0]
	v_pk_mul_f32 v[34:35], v[16:17], v[252:253] op_sel_hi:[1,0]
	v_cvt_pk_bf16_f32 v16, v28, v29
	v_cvt_pk_bf16_f32 v17, v30, v31
	v_cvt_pk_bf16_f32 v18, v24, v25
	v_cvt_pk_bf16_f32 v19, v26, v27
	v_cvt_pk_bf16_f32 v20, v20, v21
	v_cvt_pk_bf16_f32 v21, v22, v23
	v_cvt_pk_bf16_f32 v22, v34, v35
	v_cvt_pk_bf16_f32 v23, v36, v37
	global_store_dwordx4 v[32:33], v[16:19], off
	global_store_dwordx4 v[32:33], v[20:23], off offset:256
	s_nop 0
	v_add_u32_e32 v17, 0xb0, v144
	s_nop 0
	v_fmamk_f32 v16, v249, 0x3a000000, v158
	v_rsq_f32_e32 v252, v16
	s_nop 0
	v_mul_f32_e32 v252, v252, v145
	v_mad_i64_i32 v[16:17], s[4:5], v17, s82, v[148:149]
	v_lshl_add_u64 v[16:17], v[16:17], 0, v[146:147]
	v_pk_mul_f32 v[14:15], v[14:15], v[252:253] op_sel_hi:[1,0]
	v_pk_mul_f32 v[12:13], v[12:13], v[252:253] op_sel_hi:[1,0]
	v_pk_mul_f32 v[10:11], v[10:11], v[252:253] op_sel_hi:[1,0]
	v_pk_mul_f32 v[8:9], v[8:9], v[252:253] op_sel_hi:[1,0]
	s_andn2_b64 vcc, exec, s[0:1]
	v_pk_mul_f32 v[6:7], v[6:7], v[252:253] op_sel_hi:[1,0]
	v_pk_mul_f32 v[4:5], v[4:5], v[252:253] op_sel_hi:[1,0]
	v_pk_mul_f32 v[20:21], v[2:3], v[252:253] op_sel_hi:[1,0]
	v_pk_mul_f32 v[18:19], v[0:1], v[252:253] op_sel_hi:[1,0]
	v_cvt_pk_bf16_f32 v0, v12, v13
	v_cvt_pk_bf16_f32 v1, v14, v15
	v_cvt_pk_bf16_f32 v2, v8, v9
	v_cvt_pk_bf16_f32 v3, v10, v11
	s_mov_b64 s[0:1], -1
	v_cvt_pk_bf16_f32 v4, v4, v5
	v_cvt_pk_bf16_f32 v5, v6, v7
	v_cvt_pk_bf16_f32 v6, v18, v19
	v_cvt_pk_bf16_f32 v7, v20, v21
	global_store_dwordx4 v[16:17], v[0:3], off
	global_store_dwordx4 v[16:17], v[4:7], off offset:256
	s_cbranch_vccnz .LBB0_148
	s_andn2_b64 vcc, exec, s[10:11]
	s_cbranch_vccnz .LBB0_147
	s_barrier
	s_branch .LBB0_147

.LBB0_560:
	s_ashr_i32 s37, s36, 31
	s_lshl_b64 s[38:39], s[36:37], 20
	s_add_u32 s38, s33, s38
	s_addc_u32 s39, s48, s39
	s_and_b64 s[40:41], s[0:1], exec
	s_cselect_b32 s37, s39, s43
	s_cselect_b32 s79, s38, s42
	s_ashr_i32 s35, s34, 31
	s_lshl_b64 s[40:41], s[34:35], 20
	s_add_u32 s40, s49, s40
	s_addc_u32 s41, s50, s41
	s_and_b64 s[46:47], s[0:1], exec
	s_cselect_b32 s35, s41, s45
	s_cselect_b32 s80, s40, s44
	s_add_u32 s42, s42, 0x80080
	s_addc_u32 s43, s43, 0
	s_add_u32 s81, s44, 0x100
	v_mov_b32_e32 v0, 0
	s_addc_u32 s82, s45, 0
	s_mov_b32 s83, -2
	v_mov_b32_e32 v1, v0
	v_mov_b32_e32 v2, v0
	v_mov_b32_e32 v3, v0
	v_mov_b32_e32 v4, v0
	v_mov_b32_e32 v5, v0
	v_mov_b32_e32 v6, v0
	v_mov_b32_e32 v7, v0
	v_mov_b32_e32 v16, v0
	v_mov_b32_e32 v17, v0
	v_mov_b32_e32 v18, v0
	v_mov_b32_e32 v19, v0
	v_mov_b32_e32 v20, v0
	v_mov_b32_e32 v21, v0
	v_mov_b32_e32 v22, v0
	v_mov_b32_e32 v23, v0
	v_mov_b32_e32 v32, v0
	v_mov_b32_e32 v33, v0
	v_mov_b32_e32 v34, v0
	v_mov_b32_e32 v35, v0
	v_mov_b32_e32 v36, v0
	v_mov_b32_e32 v37, v0
	v_mov_b32_e32 v38, v0
	v_mov_b32_e32 v39, v0
	v_mov_b32_e32 v48, v0
	v_mov_b32_e32 v49, v0
	v_mov_b32_e32 v50, v0
	v_mov_b32_e32 v51, v0
	v_mov_b32_e32 v52, v0
	v_mov_b32_e32 v53, v0
	v_mov_b32_e32 v54, v0
	v_mov_b32_e32 v55, v0
	v_mov_b32_e32 v8, v0
	v_mov_b32_e32 v9, v0
	v_mov_b32_e32 v10, v0
	v_mov_b32_e32 v11, v0
	v_mov_b32_e32 v12, v0
	v_mov_b32_e32 v13, v0
	v_mov_b32_e32 v14, v0
	v_mov_b32_e32 v15, v0
	v_mov_b32_e32 v24, v0
	v_mov_b32_e32 v25, v0
	v_mov_b32_e32 v26, v0
	v_mov_b32_e32 v27, v0
	v_mov_b32_e32 v28, v0
	v_mov_b32_e32 v29, v0
	v_mov_b32_e32 v30, v0
	v_mov_b32_e32 v31, v0
	v_mov_b32_e32 v40, v0
	v_mov_b32_e32 v41, v0
	v_mov_b32_e32 v42, v0
	v_mov_b32_e32 v43, v0
	v_mov_b32_e32 v44, v0
	v_mov_b32_e32 v45, v0
	v_mov_b32_e32 v46, v0
	v_mov_b32_e32 v47, v0
	v_mov_b32_e32 v56, v0
	v_mov_b32_e32 v57, v0
	v_mov_b32_e32 v58, v0
	v_mov_b32_e32 v59, v0
	v_mov_b32_e32 v60, v0
	v_mov_b32_e32 v61, v0
	v_mov_b32_e32 v62, v0
	v_mov_b32_e32 v63, v0
	v_mov_b32_e32 v64, v0
	v_mov_b32_e32 v65, v0
	v_mov_b32_e32 v66, v0
	v_mov_b32_e32 v67, v0
	v_mov_b32_e32 v68, v0
	v_mov_b32_e32 v69, v0
	v_mov_b32_e32 v70, v0
	v_mov_b32_e32 v71, v0
	v_mov_b32_e32 v80, v0
	v_mov_b32_e32 v81, v0
	v_mov_b32_e32 v82, v0
	v_mov_b32_e32 v83, v0
	v_mov_b32_e32 v84, v0
	v_mov_b32_e32 v85, v0
	v_mov_b32_e32 v86, v0
	v_mov_b32_e32 v87, v0
	v_mov_b32_e32 v96, v0
	v_mov_b32_e32 v97, v0
	v_mov_b32_e32 v98, v0
	v_mov_b32_e32 v99, v0
	v_mov_b32_e32 v100, v0
	v_mov_b32_e32 v101, v0
	v_mov_b32_e32 v102, v0
	v_mov_b32_e32 v103, v0
	v_mov_b32_e32 v112, v0
	v_mov_b32_e32 v113, v0
	v_mov_b32_e32 v114, v0
	v_mov_b32_e32 v115, v0
	v_mov_b32_e32 v116, v0
	v_mov_b32_e32 v117, v0
	v_mov_b32_e32 v118, v0
	v_mov_b32_e32 v119, v0
	v_mov_b32_e32 v72, v0
	v_mov_b32_e32 v73, v0
	v_mov_b32_e32 v74, v0
	v_mov_b32_e32 v75, v0
	v_mov_b32_e32 v76, v0
	v_mov_b32_e32 v77, v0
	v_mov_b32_e32 v78, v0
	v_mov_b32_e32 v79, v0
	v_mov_b32_e32 v88, v0
	v_mov_b32_e32 v89, v0
	v_mov_b32_e32 v90, v0
	v_mov_b32_e32 v91, v0
	v_mov_b32_e32 v92, v0
	v_mov_b32_e32 v93, v0
	v_mov_b32_e32 v94, v0
	v_mov_b32_e32 v95, v0
	v_mov_b32_e32 v104, v0
	v_mov_b32_e32 v105, v0
	v_mov_b32_e32 v106, v0
	v_mov_b32_e32 v107, v0
	v_mov_b32_e32 v108, v0
	v_mov_b32_e32 v109, v0
	v_mov_b32_e32 v110, v0
	v_mov_b32_e32 v111, v0
	v_mov_b32_e32 v120, v0
	v_mov_b32_e32 v121, v0
	v_mov_b32_e32 v122, v0
	v_mov_b32_e32 v123, v0
	v_mov_b32_e32 v124, v0
	v_mov_b32_e32 v125, v0
	v_mov_b32_e32 v126, v0
	v_mov_b32_e32 v127, v0
	v_lshl_add_u32 v250, s4, 8, v152
	v_ashrrev_i32_e32 v251, 31, v250
	v_lshl_add_u64 v[250:251], v[250:251], 2, s[16:17]
	global_load_dword v242, v[250:251], off
	global_load_dword v243, v[250:251], off offset:64
	global_load_dword v244, v[250:251], off offset:128
	global_load_dword v245, v[250:251], off offset:192
	global_load_dword v246, v[250:251], off offset:512
	global_load_dword v247, v[250:251], off offset:576
	global_load_dword v248, v[250:251], off offset:640
	global_load_dword v249, v[250:251], off offset:704

.LBB0_564:
	v_lshl_add_u32 v150, s4, 8, v152
	v_ashrrev_i32_e32 v151, 31, v150
	v_lshl_add_u64 v[144:145], v[150:151], 2, s[16:17]
	s_nop 0
	v_lshl_or_b32 v146, s5, 8, v154
	s_cmp_lt_i32 s5, 8
	v_ashrrev_i32_e32 v147, 31, v146
	s_cselect_b64 vcc, -1, 0
	v_lshlrev_b64 v[148:149], 1, v[146:147]
	v_cndmask_b32_e32 v161, 1.0, v160, vcc
	v_lshlrev_b64 v[164:165], 14, v[150:151]
	v_or_b32_e32 v162, 16, v150
	s_nop 0
	v_fmamk_f32 v146, v242, 0x3a000000, v158
	v_rsq_f32_e32 v252, v146
	s_nop 0
	v_mul_f32_e32 v252, v252, v161
	v_ashrrev_i32_e32 v163, 31, v162
	v_lshl_add_u64 v[146:147], s[10:11], 0, v[164:165]
	v_lshl_add_u64 v[146:147], v[146:147], 0, v[148:149]
	v_lshl_add_u64 v[164:165], v[162:163], 2, s[16:17]
	v_pk_mul_f32 v[126:127], v[126:127], v[252:253] op_sel_hi:[1,0]
	v_pk_mul_f32 v[124:125], v[124:125], v[252:253] op_sel_hi:[1,0]
	v_pk_mul_f32 v[122:123], v[122:123], v[252:253] op_sel_hi:[1,0]
	v_pk_mul_f32 v[120:121], v[120:121], v[252:253] op_sel_hi:[1,0]
	v_pk_mul_f32 v[118:119], v[118:119], v[252:253] op_sel_hi:[1,0]
	v_pk_mul_f32 v[116:117], v[116:117], v[252:253] op_sel_hi:[1,0]
	v_pk_mul_f32 v[168:169], v[114:115], v[252:253] op_sel_hi:[1,0]
	v_pk_mul_f32 v[166:167], v[112:113], v[252:253] op_sel_hi:[1,0]
	v_cvt_pk_bf16_f32 v112, v124, v125
	v_cvt_pk_bf16_f32 v113, v126, v127
	v_cvt_pk_bf16_f32 v114, v120, v121
	v_cvt_pk_bf16_f32 v115, v122, v123
	v_cvt_pk_bf16_f32 v116, v116, v117
	v_cvt_pk_bf16_f32 v117, v118, v119
	v_cvt_pk_bf16_f32 v118, v166, v167
	v_cvt_pk_bf16_f32 v119, v168, v169
	global_store_dwordx4 v[146:147], v[112:115], off
	global_store_dwordx4 v[146:147], v[116:119], off offset:256
	s_nop 0
	v_or_b32_e32 v112, 32, v150
	v_ashrrev_i32_e32 v113, 31, v112
	v_lshl_add_u64 v[116:117], v[112:113], 2, s[16:17]
	s_nop 0
	v_fmamk_f32 v114, v243, 0x3a000000, v158
	v_rsq_f32_e32 v252, v114
	s_nop 0
	v_mul_f32_e32 v252, v252, v161
	v_lshlrev_b64 v[114:115], 14, v[162:163]
	v_lshl_add_u64 v[114:115], s[10:11], 0, v[114:115]
	v_lshl_add_u64 v[114:115], v[114:115], 0, v[148:149]
	v_pk_mul_f32 v[110:111], v[110:111], v[252:253] op_sel_hi:[1,0]
	v_pk_mul_f32 v[108:109], v[108:109], v[252:253] op_sel_hi:[1,0]
	v_pk_mul_f32 v[106:107], v[106:107], v[252:253] op_sel_hi:[1,0]
	v_pk_mul_f32 v[104:105], v[104:105], v[252:253] op_sel_hi:[1,0]
	v_pk_mul_f32 v[102:103], v[102:103], v[252:253] op_sel_hi:[1,0]
	v_pk_mul_f32 v[100:101], v[100:101], v[252:253] op_sel_hi:[1,0]
	v_pk_mul_f32 v[120:121], v[98:99], v[252:253] op_sel_hi:[1,0]
	v_pk_mul_f32 v[118:119], v[96:97], v[252:253] op_sel_hi:[1,0]
	v_cvt_pk_bf16_f32 v96, v108, v109
	v_cvt_pk_bf16_f32 v97, v110, v111
	v_cvt_pk_bf16_f32 v98, v104, v105
	v_cvt_pk_bf16_f32 v99, v106, v107
	v_cvt_pk_bf16_f32 v100, v100, v101
	v_cvt_pk_bf16_f32 v101, v102, v103
	v_cvt_pk_bf16_f32 v102, v118, v119
	v_cvt_pk_bf16_f32 v103, v120, v121
	global_store_dwordx4 v[114:115], v[96:99], off
	global_store_dwordx4 v[114:115], v[100:103], off offset:256
	s_nop 0
	v_or_b32_e32 v96, 48, v150
	v_ashrrev_i32_e32 v97, 31, v96
	v_lshl_add_u64 v[100:101], v[96:97], 2, s[16:17]
	s_nop 0
	v_fmamk_f32 v98, v244, 0x3a000000, v158
	v_rsq_f32_e32 v252, v98
	s_nop 0
	v_mul_f32_e32 v252, v252, v161
	v_lshlrev_b64 v[98:99], 14, v[112:113]
	v_lshl_add_u64 v[98:99], s[10:11], 0, v[98:99]
	v_lshl_add_u64 v[98:99], v[98:99], 0, v[148:149]
	v_pk_mul_f32 v[94:95], v[94:95], v[252:253] op_sel_hi:[1,0]
	v_pk_mul_f32 v[92:93], v[92:93], v[252:253] op_sel_hi:[1,0]
	v_pk_mul_f32 v[90:91], v[90:91], v[252:253] op_sel_hi:[1,0]
	v_pk_mul_f32 v[88:89], v[88:89], v[252:253] op_sel_hi:[1,0]
	v_pk_mul_f32 v[86:87], v[86:87], v[252:253] op_sel_hi:[1,0]
	v_pk_mul_f32 v[84:85], v[84:85], v[252:253] op_sel_hi:[1,0]
	v_pk_mul_f32 v[104:105], v[82:83], v[252:253] op_sel_hi:[1,0]
	v_pk_mul_f32 v[102:103], v[80:81], v[252:253] op_sel_hi:[1,0]
	v_cvt_pk_bf16_f32 v80, v92, v93
	v_cvt_pk_bf16_f32 v81, v94, v95
	v_cvt_pk_bf16_f32 v82, v88, v89
	v_cvt_pk_bf16_f32 v83, v90, v91
	v_cvt_pk_bf16_f32 v84, v84, v85
	v_cvt_pk_bf16_f32 v85, v86, v87
	v_cvt_pk_bf16_f32 v86, v102, v103
	v_cvt_pk_bf16_f32 v87, v104, v105
	global_store_dwordx4 v[98:99], v[80:83], off
	global_store_dwordx4 v[98:99], v[84:87], off offset:256
	s_nop 0
	s_nop 0
	v_fmamk_f32 v80, v245, 0x3a000000, v158
	v_rsq_f32_e32 v252, v80
	s_nop 0
	v_mul_f32_e32 v252, v252, v161
	v_lshlrev_b64 v[80:81], 14, v[96:97]
	v_lshl_add_u64 v[80:81], s[10:11], 0, v[80:81]
	v_lshl_add_u64 v[80:81], v[80:81], 0, v[148:149]
	v_pk_mul_f32 v[78:79], v[78:79], v[252:253] op_sel_hi:[1,0]
	v_pk_mul_f32 v[76:77], v[76:77], v[252:253] op_sel_hi:[1,0]
	v_pk_mul_f32 v[74:75], v[74:75], v[252:253] op_sel_hi:[1,0]
	v_pk_mul_f32 v[72:73], v[72:73], v[252:253] op_sel_hi:[1,0]
	v_pk_mul_f32 v[70:71], v[70:71], v[252:253] op_sel_hi:[1,0]
	v_pk_mul_f32 v[68:69], v[68:69], v[252:253] op_sel_hi:[1,0]
	v_pk_mul_f32 v[84:85], v[66:67], v[252:253] op_sel_hi:[1,0]
	v_pk_mul_f32 v[82:83], v[64:65], v[252:253] op_sel_hi:[1,0]
	v_cvt_pk_bf16_f32 v64, v76, v77
	v_cvt_pk_bf16_f32 v65, v78, v79
	v_cvt_pk_bf16_f32 v66, v72, v73
	v_cvt_pk_bf16_f32 v67, v74, v75
	v_cvt_pk_bf16_f32 v68, v68, v69
	v_cvt_pk_bf16_f32 v69, v70, v71
	v_cvt_pk_bf16_f32 v70, v82, v83
	v_cvt_pk_bf16_f32 v71, v84, v85
	global_store_dwordx4 v[80:81], v[64:67], off
	global_store_dwordx4 v[80:81], v[68:71], off offset:256
	s_nop 0
	s_nop 0
	v_fmamk_f32 v64, v246, 0x3a000000, v158
	v_rsq_f32_e32 v252, v64
	s_nop 0
	v_mul_f32_e32 v252, v252, v161
	v_lshl_add_u64 v[64:65], v[146:147], 0, s[20:21]
	v_add_co_u32_e32 v66, vcc, s75, v146
	v_addc_co_u32_e32 v67, vcc, 0, v147, vcc
	v_pk_mul_f32 v[62:63], v[62:63], v[252:253] op_sel_hi:[1,0]
	v_pk_mul_f32 v[60:61], v[60:61], v[252:253] op_sel_hi:[1,0]
	v_pk_mul_f32 v[58:59], v[58:59], v[252:253] op_sel_hi:[1,0]
	v_pk_mul_f32 v[56:57], v[56:57], v[252:253] op_sel_hi:[1,0]
	v_pk_mul_f32 v[54:55], v[54:55], v[252:253] op_sel_hi:[1,0]
	v_pk_mul_f32 v[52:53], v[52:53], v[252:253] op_sel_hi:[1,0]
	v_pk_mul_f32 v[70:71], v[50:51], v[252:253] op_sel_hi:[1,0]
	v_pk_mul_f32 v[68:69], v[48:49], v[252:253] op_sel_hi:[1,0]
	v_cvt_pk_bf16_f32 v48, v60, v61
	v_cvt_pk_bf16_f32 v49, v62, v63
	v_cvt_pk_bf16_f32 v50, v56, v57
	v_cvt_pk_bf16_f32 v51, v58, v59
	v_cvt_pk_bf16_f32 v52, v52, v53
	v_cvt_pk_bf16_f32 v53, v54, v55
	v_cvt_pk_bf16_f32 v54, v68, v69
	v_cvt_pk_bf16_f32 v55, v70, v71
	global_store_dwordx4 v[66:67], v[48:51], off
	global_store_dwordx4 v[64:65], v[52:55], off offset:256
	s_nop 0
	s_nop 0
	v_fmamk_f32 v48, v247, 0x3a000000, v158
	v_rsq_f32_e32 v252, v48
	s_nop 0
	v_mul_f32_e32 v252, v252, v161
	v_lshl_add_u64 v[48:49], v[146:147], 0, s[22:23]
	v_add_co_u32_e32 v50, vcc, s76, v146
	v_addc_co_u32_e32 v51, vcc, 0, v147, vcc
	v_pk_mul_f32 v[46:47], v[46:47], v[252:253] op_sel_hi:[1,0]
	v_pk_mul_f32 v[44:45], v[44:45], v[252:253] op_sel_hi:[1,0]
	v_pk_mul_f32 v[42:43], v[42:43], v[252:253] op_sel_hi:[1,0]
	v_pk_mul_f32 v[40:41], v[40:41], v[252:253] op_sel_hi:[1,0]
	v_pk_mul_f32 v[38:39], v[38:39], v[252:253] op_sel_hi:[1,0]
	v_pk_mul_f32 v[36:37], v[36:37], v[252:253] op_sel_hi:[1,0]
	v_pk_mul_f32 v[54:55], v[34:35], v[252:253] op_sel_hi:[1,0]
	v_pk_mul_f32 v[52:53], v[32:33], v[252:253] op_sel_hi:[1,0]
	v_cvt_pk_bf16_f32 v32, v44, v45
	v_cvt_pk_bf16_f32 v33, v46, v47
	v_cvt_pk_bf16_f32 v34, v40, v41
	v_cvt_pk_bf16_f32 v35, v42, v43
	v_cvt_pk_bf16_f32 v36, v36, v37
	v_cvt_pk_bf16_f32 v37, v38, v39
	v_cvt_pk_bf16_f32 v38, v52, v53
	v_cvt_pk_bf16_f32 v39, v54, v55
	global_store_dwordx4 v[50:51], v[32:35], off
	global_store_dwordx4 v[48:49], v[36:39], off offset:256
	s_nop 0
	s_nop 0
	v_fmamk_f32 v32, v248, 0x3a000000, v158
	v_rsq_f32_e32 v252, v32
	s_nop 0
	v_mul_f32_e32 v252, v252, v161
	v_lshl_add_u64 v[32:33], v[146:147], 0, s[24:25]
	v_add_co_u32_e32 v34, vcc, s77, v146
	v_addc_co_u32_e32 v35, vcc, 0, v147, vcc
	v_pk_mul_f32 v[30:31], v[30:31], v[252:253] op_sel_hi:[1,0]
	v_pk_mul_f32 v[28:29], v[28:29], v[252:253] op_sel_hi:[1,0]
	v_pk_mul_f32 v[26:27], v[26:27], v[252:253] op_sel_hi:[1,0]
	v_pk_mul_f32 v[24:25], v[24:25], v[252:253] op_sel_hi:[1,0]
	v_pk_mul_f32 v[22:23], v[22:23], v[252:253] op_sel_hi:[1,0]
	v_pk_mul_f32 v[20:21], v[20:21], v[252:253] op_sel_hi:[1,0]
	v_pk_mul_f32 v[38:39], v[18:19], v[252:253] op_sel_hi:[1,0]
	v_pk_mul_f32 v[36:37], v[16:17], v[252:253] op_sel_hi:[1,0]
	v_cvt_pk_bf16_f32 v16, v28, v29
	v_cvt_pk_bf16_f32 v17, v30, v31
	v_cvt_pk_bf16_f32 v18, v24, v25
	v_cvt_pk_bf16_f32 v19, v26, v27
	v_cvt_pk_bf16_f32 v20, v20, v21
	v_cvt_pk_bf16_f32 v21, v22, v23
	v_cvt_pk_bf16_f32 v22, v36, v37
	v_cvt_pk_bf16_f32 v23, v38, v39
	global_store_dwordx4 v[34:35], v[16:19], off
	global_store_dwordx4 v[32:33], v[20:23], off offset:256
	s_nop 0
	s_nop 0
	v_fmamk_f32 v16, v249, 0x3a000000, v158
	v_rsq_f32_e32 v252, v16
	s_nop 0
	v_mul_f32_e32 v252, v252, v161
	v_lshl_add_u64 v[16:17], v[146:147], 0, s[26:27]
	v_add_co_u32_e32 v18, vcc, s78, v146
	v_addc_co_u32_e32 v19, vcc, 0, v147, vcc
	v_pk_mul_f32 v[14:15], v[14:15], v[252:253] op_sel_hi:[1,0]
	v_pk_mul_f32 v[12:13], v[12:13], v[252:253] op_sel_hi:[1,0]
	v_pk_mul_f32 v[10:11], v[10:11], v[252:253] op_sel_hi:[1,0]
	v_pk_mul_f32 v[8:9], v[8:9], v[252:253] op_sel_hi:[1,0]
	s_andn2_b64 vcc, exec, s[0:1]
	v_pk_mul_f32 v[6:7], v[6:7], v[252:253] op_sel_hi:[1,0]
	v_pk_mul_f32 v[4:5], v[4:5], v[252:253] op_sel_hi:[1,0]
	v_pk_mul_f32 v[22:23], v[2:3], v[252:253] op_sel_hi:[1,0]
	v_pk_mul_f32 v[20:21], v[0:1], v[252:253] op_sel_hi:[1,0]
	v_cvt_pk_bf16_f32 v0, v12, v13
	v_cvt_pk_bf16_f32 v1, v14, v15
	v_cvt_pk_bf16_f32 v2, v8, v9
	v_cvt_pk_bf16_f32 v3, v10, v11
	s_mov_b64 s[0:1], -1
	v_cvt_pk_bf16_f32 v4, v4, v5
	v_cvt_pk_bf16_f32 v5, v6, v7
	v_cvt_pk_bf16_f32 v6, v20, v21
	v_cvt_pk_bf16_f32 v7, v22, v23
	global_store_dwordx4 v[18:19], v[0:3], off
	global_store_dwordx4 v[16:17], v[4:7], off offset:256
	s_cbranch_vccnz .LBB0_553
	s_andn2_b64 vcc, exec, s[6:7]
	s_cbranch_vccnz .LBB0_552
	s_barrier
	s_branch .LBB0_552
